# top-k radix select: upper bound (largest key) and lower bound (min of 256 group maxima) decide candidate bits outside the bracket without a counting pass
# speedup vs baseline: 1.0186x; 1.0009x over previous
; #define TK_GRP(g) { const int c0 = __popcll(__ballot(u[4 * (g)] >= cand)), c1 = __popcll(__ballot(u[4 * (g) + 1] >= cand)), c2 = __popcll(__ballot(u[4 * (g) + 2] >= cand)), c3 = __popcll(__ballot(u[4 * (g) + 3] >= cand)); cnt += (c0 + c1) + (c2 + c3); }
; __device__ __forceinline__ void indexer_unit(const Args& a, LAS unsigned char* lds, LAS unsigned long long* maskl, int b, int qblk, int wave, int lane) {
;     ...
;             for (int g = 0; g < 8; ++g) if (4 * g < nr) {
; #pragma unroll
;                 for (int k4 = 0; k4 < 4; ++k4) { const int r = 4 * g + k4; const int idx = 64 * r + lane; const unsigned bits = __builtin_bit_cast(unsigned, sc[q * 2048 + idx]);
;                     const unsigned k = bits ^ (((unsigned)((int)bits >> 31)) | 0x80000000u); u[r] = idx < n ? k : 0u; } }
;             unsigned T = 0u; bool exact = false; const int ng = (nr + 3) >> 2;
; #pragma unroll 1
;     ...
;                 const unsigned cand = T | (1u << bit); int cnt = 0;
;     ...
;                 switch (ng) {
;                     case 8: TK_GRP(7) [[fallthrough]];
;                     case 7: TK_GRP(6) [[fallthrough]];
;                     case 6: TK_GRP(5) [[fallthrough]];
;                     case 5: TK_GRP(4) [[fallthrough]];
;                     case 4: TK_GRP(3) [[fallthrough]];
;                     case 3: TK_GRP(2) [[fallthrough]];
;                     case 2: TK_GRP(1) [[fallthrough]];
;                     default: TK_GRP(0)
;                 }
;     ...
;                 if (cnt >= 256) { T = cand; if (cnt == 256) { exact = true; break; } }
;             }
.Ltk_ld_done:
	v_max_u32_e32 v26, v32, v36
	v_max_u32_e32 v27, v33, v37
	v_max_u32_e32 v28, v34, v38
	v_max_u32_e32 v29, v35, v39
	s_cmp_lt_u32 s21, 2
	s_cbranch_scc1 .Ltk_bd_done
	v_max_u32_e32 v26, v40, v26
	v_max_u32_e32 v27, v41, v27
	v_max_u32_e32 v28, v42, v28
	v_max_u32_e32 v29, v43, v29
	v_max_u32_e32 v26, v44, v26
	v_max_u32_e32 v27, v45, v27
	v_max_u32_e32 v28, v46, v28
	v_max_u32_e32 v29, v47, v29
	s_cmp_lt_u32 s21, 3
	s_cbranch_scc1 .Ltk_bd_done
	v_max_u32_e32 v26, v48, v26
	v_max_u32_e32 v27, v49, v27
	v_max_u32_e32 v28, v50, v28
	v_max_u32_e32 v29, v51, v29
	v_max_u32_e32 v26, v52, v26
	v_max_u32_e32 v27, v53, v27
	v_max_u32_e32 v28, v54, v28
	v_max_u32_e32 v29, v55, v29
	s_cmp_lt_u32 s21, 4
	s_cbranch_scc1 .Ltk_bd_done
	v_max_u32_e32 v26, v56, v26
	v_max_u32_e32 v27, v57, v27
	v_max_u32_e32 v28, v58, v28
	v_max_u32_e32 v29, v59, v29
	v_max_u32_e32 v26, v60, v26
	v_max_u32_e32 v27, v61, v27
	v_max_u32_e32 v28, v62, v28
	v_max_u32_e32 v29, v63, v29
.Ltk_bd_done:
	v_min_u32_e32 v30, v26, v27
	v_min_u32_e32 v31, v28, v29
	v_max_u32_e32 v25, v26, v27
	v_max_u32_e32 v26, v28, v29
	v_min_u32_e32 v30, v30, v31
	v_max_u32_e32 v25, v25, v26
	s_nop 1
	v_min_u32_dpp v31, v30, v30 quad_perm:[1,0,3,2] row_mask:0xf bank_mask:0xf
	v_max_u32_dpp v26, v25, v25 quad_perm:[1,0,3,2] row_mask:0xf bank_mask:0xf
	s_nop 1
	v_mov_b32_e32 v30, v31
	v_mov_b32_e32 v25, v26
	s_nop 1
	v_min_u32_dpp v31, v30, v30 quad_perm:[2,3,0,1] row_mask:0xf bank_mask:0xf
	v_max_u32_dpp v26, v25, v25 quad_perm:[2,3,0,1] row_mask:0xf bank_mask:0xf
	s_nop 1
	v_mov_b32_e32 v30, v31
	v_mov_b32_e32 v25, v26
	s_nop 1
	v_min_u32_dpp v31, v30, v30 row_half_mirror row_mask:0xf bank_mask:0xf
	v_max_u32_dpp v26, v25, v25 row_half_mirror row_mask:0xf bank_mask:0xf
	s_nop 1
	v_mov_b32_e32 v30, v31
	v_mov_b32_e32 v25, v26
	s_nop 1
	v_min_u32_dpp v31, v30, v30 row_mirror row_mask:0xf bank_mask:0xf
	v_max_u32_dpp v26, v25, v25 row_mirror row_mask:0xf bank_mask:0xf
	s_nop 1
	v_mov_b32_e32 v30, v31
	v_mov_b32_e32 v25, v26
	s_nop 1
	v_readlane_b32 s16, v25, 0
	v_readlane_b32 s17, v25, 16
	v_readlane_b32 s22, v25, 32
	v_readlane_b32 s23, v25, 48
	s_max_u32 s18, s16, s17
	s_max_u32 s22, s22, s23
	s_max_u32 s18, s18, s22
	v_readlane_b32 s16, v30, 0
	v_readlane_b32 s17, v30, 16
	v_readlane_b32 s22, v30, 32
	v_readlane_b32 s23, v30, 48
	s_min_u32 s16, s16, s17
	s_min_u32 s22, s22, s23
	s_min_u32 s23, s16, s22
	s_mov_b32 s10, 0
	s_mov_b32 s11, 31
.Ltk_bit:
	s_lshl_b32 s12, 1, s11
	s_or_b32 s13, s10, s12
	s_cmp_gt_u32 s13, s18
	s_cbranch_scc1 .Ltk_nxt
	s_cmp_le_u32 s13, s23
	s_cbranch_scc1 .Ltk_acc
	v_mov_b32_e32 v24, 0
	v_cmp_le_u32_e64 s[24:25], s13, v32
	v_cmp_le_u32_e64 s[26:27], s13, v33
	v_cmp_le_u32_e64 s[28:29], s13, v34
	v_cmp_le_u32_e64 s[30:31], s13, v35
	v_cmp_le_u32_e64 s[34:35], s13, v36
	v_cmp_le_u32_e64 s[36:37], s13, v37
	v_cmp_le_u32_e64 s[38:39], s13, v38
	v_cmp_le_u32_e64 s[40:41], s13, v39
	s_bcnt1_i32_b64 s42, s[24:25]
	s_bcnt1_i32_b64 s43, s[26:27]
	s_bcnt1_i32_b64 s44, s[28:29]
	s_bcnt1_i32_b64 s45, s[30:31]
	s_bcnt1_i32_b64 s46, s[34:35]
	s_bcnt1_i32_b64 s47, s[36:37]
	s_bcnt1_i32_b64 s48, s[38:39]
	s_bcnt1_i32_b64 s49, s[40:41]
	s_add_i32 s14, s42, s43
	v_add_u32_e32 v24, s44, v24
	v_add_u32_e32 v24, s45, v24
	v_add_u32_e32 v24, s46, v24
	v_add_u32_e32 v24, s47, v24
	v_add_u32_e32 v24, s48, v24
	v_add_u32_e32 v24, s49, v24
	s_cmp_lt_u32 s21, 2
	s_cbranch_scc1 .Ltk_dec
	v_cmp_le_u32_e64 s[24:25], s13, v40
	v_cmp_le_u32_e64 s[26:27], s13, v41
	v_cmp_le_u32_e64 s[28:29], s13, v42
	v_cmp_le_u32_e64 s[30:31], s13, v43
	v_cmp_le_u32_e64 s[34:35], s13, v44
	v_cmp_le_u32_e64 s[36:37], s13, v45
	v_cmp_le_u32_e64 s[38:39], s13, v46
	v_cmp_le_u32_e64 s[40:41], s13, v47
	s_bcnt1_i32_b64 s42, s[24:25]
	s_bcnt1_i32_b64 s43, s[26:27]
	s_bcnt1_i32_b64 s44, s[28:29]
	s_bcnt1_i32_b64 s45, s[30:31]
	s_bcnt1_i32_b64 s46, s[34:35]
	s_bcnt1_i32_b64 s47, s[36:37]
	s_bcnt1_i32_b64 s48, s[38:39]
	s_bcnt1_i32_b64 s49, s[40:41]
	s_add_i32 s14, s14, s42
	s_add_i32 s14, s14, s43
	v_add_u32_e32 v24, s44, v24
	v_add_u32_e32 v24, s45, v24
	v_add_u32_e32 v24, s46, v24
	v_add_u32_e32 v24, s47, v24
	v_add_u32_e32 v24, s48, v24
	v_add_u32_e32 v24, s49, v24
	s_cmp_lt_u32 s21, 3
	s_cbranch_scc1 .Ltk_dec
	v_cmp_le_u32_e64 s[24:25], s13, v48
	v_cmp_le_u32_e64 s[26:27], s13, v49
	v_cmp_le_u32_e64 s[28:29], s13, v50
	v_cmp_le_u32_e64 s[30:31], s13, v51
	v_cmp_le_u32_e64 s[34:35], s13, v52
	v_cmp_le_u32_e64 s[36:37], s13, v53
	v_cmp_le_u32_e64 s[38:39], s13, v54
	v_cmp_le_u32_e64 s[40:41], s13, v55
	s_bcnt1_i32_b64 s42, s[24:25]
	s_bcnt1_i32_b64 s43, s[26:27]
	s_bcnt1_i32_b64 s44, s[28:29]
	s_bcnt1_i32_b64 s45, s[30:31]
	s_bcnt1_i32_b64 s46, s[34:35]
	s_bcnt1_i32_b64 s47, s[36:37]
	s_bcnt1_i32_b64 s48, s[38:39]
	s_bcnt1_i32_b64 s49, s[40:41]
	s_add_i32 s14, s14, s42
	s_add_i32 s14, s14, s43
	v_add_u32_e32 v24, s44, v24
	v_add_u32_e32 v24, s45, v24
	v_add_u32_e32 v24, s46, v24
	v_add_u32_e32 v24, s47, v24
	v_add_u32_e32 v24, s48, v24
	v_add_u32_e32 v24, s49, v24
	s_cmp_lt_u32 s21, 4
	s_cbranch_scc1 .Ltk_dec
	v_cmp_le_u32_e64 s[24:25], s13, v56
	v_cmp_le_u32_e64 s[26:27], s13, v57
	v_cmp_le_u32_e64 s[28:29], s13, v58
	v_cmp_le_u32_e64 s[30:31], s13, v59
	v_cmp_le_u32_e64 s[34:35], s13, v60
	v_cmp_le_u32_e64 s[36:37], s13, v61
	v_cmp_le_u32_e64 s[38:39], s13, v62
	v_cmp_le_u32_e64 s[40:41], s13, v63
	s_bcnt1_i32_b64 s42, s[24:25]
	s_bcnt1_i32_b64 s43, s[26:27]
	s_bcnt1_i32_b64 s44, s[28:29]
	s_bcnt1_i32_b64 s45, s[30:31]
	s_bcnt1_i32_b64 s46, s[34:35]
	s_bcnt1_i32_b64 s47, s[36:37]
	s_bcnt1_i32_b64 s48, s[38:39]
	s_bcnt1_i32_b64 s49, s[40:41]
	s_add_i32 s14, s14, s42
	s_add_i32 s14, s14, s43
	v_add_u32_e32 v24, s44, v24
	v_add_u32_e32 v24, s45, v24
	v_add_u32_e32 v24, s46, v24
	v_add_u32_e32 v24, s47, v24
	v_add_u32_e32 v24, s48, v24
	v_add_u32_e32 v24, s49, v24
.Ltk_dec:
	s_nop 0
	v_readfirstlane_b32 s15, v24
	s_add_i32 s14, s14, s15
	s_cmpk_lt_u32 s14, 0x100
	s_cbranch_scc1 .Ltk_nxt
	s_mov_b32 s10, s13
	s_cmpk_eq_u32 s14, 0x100
	s_cbranch_scc1 .Ltk_exact
	s_branch .Ltk_nxt
.Ltk_acc:
	s_mov_b32 s10, s13
